# ring4 + drop per-iteration negm v_mov copies (half-2 MFMA C operand reads master tuple)
# speedup vs baseline: 1.0324x; 1.0032x over previous
.LBB0_400:
	v_cvt_pk_bf16_f32 v182, v148, v149
	v_cvt_pk_bf16_f32 v183, v152, v153
	v_cvt_pk_bf16_f32 v184, v154, v155
	v_cvt_pk_bf16_f32 v185, v158, v159
	v_cvt_pk_bf16_f32 v160, v150, v151
	v_cvt_pk_bf16_f32 v161, v156, v157
	v_cvt_pk_bf16_f32 v162, v162, v163
	v_cvt_pk_bf16_f32 v163, v166, v167
	s_waitcnt vmcnt(0)
	ds_write_b128 v205, v[132:135]
	ds_write_b128 v206, v[136:139]
	ds_write_b128 v207, v[128:131] offset:32768
	s_cmpk_lt_u32 s51, 0x100
	s_cselect_b32 s0, s38, s34
	s_add_i32 s3, s0, s51
	s_mul_i32 s0, s3, 0x1800
	s_mul_hi_i32 s1, s3, 0x1800
	s_add_u32 s0, s39, s0
	s_addc_u32 s1, s42, s1
	v_lshl_add_u64 v[148:149], s[0:1], 0, v[170:171]
	v_add_co_u32_e32 v152, vcc, s33, v148
	v_mad_i64_i32 v[156:157], s[0:1], s3, v195, v[180:181]
	s_nop 0
	v_addc_co_u32_e32 v153, vcc, 0, v149, vcc
	global_load_dwordx4 v[148:151], v[148:149], off
	s_nop 0
	global_load_dwordx4 v[152:155], v[152:153], off
	s_nop 0
	global_load_dwordx4 v[156:159], v[156:157], off
	ds_read_b64_tr_b16 v[186:187], v203 offset:0
	ds_read_b64_tr_b16 v[188:189], v203 offset:0x800
	ds_read_b64_tr_b16 v[214:215], v203 offset:0x200
	ds_read_b64_tr_b16 v[216:217], v203 offset:0xa00
	ds_read_b64_tr_b16 v[218:219], v203 offset:0x400
	ds_read_b64_tr_b16 v[220:221], v203 offset:0xc00
	ds_read_b64_tr_b16 v[222:223], v203 offset:0x600
	ds_read_b64_tr_b16 v[224:225], v203 offset:0xe00
	ds_read_b64_tr_b16 v[226:227], v203 offset:0x1000
	ds_read_b64_tr_b16 v[228:229], v203 offset:0x1800
	ds_read_b64_tr_b16 v[230:231], v203 offset:0x1200
	ds_read_b64_tr_b16 v[232:233], v203 offset:0x1a00
	ds_read_b64_tr_b16 v[234:235], v203 offset:0x1400
	ds_read_b64_tr_b16 v[236:237], v203 offset:0x1c00
	ds_read_b64_tr_b16 v[238:239], v203 offset:0x1600
	ds_read_b64_tr_b16 v[240:241], v203 offset:0x1e00
	s_nop 0
	s_waitcnt lgkmcnt(8)
	v_exp_f32_e32 v112, v112
	v_mfma_f32_32x32x16_bf16 v[0:15], v[144:147], v[186:189], v[0:15]
	v_exp_f32_e32 v113, v113
	v_exp_f32_e32 v114, v114
	v_exp_f32_e32 v115, v115
	v_exp_f32_e32 v116, v116
	v_exp_f32_e32 v117, v117
	v_exp_f32_e32 v118, v118
	v_exp_f32_e32 v119, v119
	v_mfma_f32_32x32x16_bf16 v[48:63], v[144:147], v[214:217], v[48:63]
	v_exp_f32_e32 v120, v120
	v_exp_f32_e32 v121, v121
	v_exp_f32_e32 v122, v122
	v_exp_f32_e32 v123, v123
	v_exp_f32_e32 v124, v124
	v_exp_f32_e32 v125, v125
	v_exp_f32_e32 v126, v126
	v_mfma_f32_32x32x16_bf16 v[32:47], v[144:147], v[218:221], v[32:47]
	v_exp_f32_e32 v127, v127
	v_mfma_f32_32x32x16_bf16 v[16:31], v[144:147], v[222:225], v[16:31]
	ds_read_b64_tr_b16 v[144:145], v203 offset:0x2000
	ds_read_b64_tr_b16 v[146:147], v203 offset:0x2800
	ds_read_b64_tr_b16 v[186:187], v203 offset:0x2200
	ds_read_b64_tr_b16 v[188:189], v203 offset:0x2a00
	ds_read_b64_tr_b16 v[214:215], v203 offset:0x2400
	ds_read_b64_tr_b16 v[216:217], v203 offset:0x2c00
	ds_read_b64_tr_b16 v[218:219], v203 offset:0x2600
	ds_read_b64_tr_b16 v[220:221], v203 offset:0x2e00
	s_waitcnt lgkmcnt(8)
	ds_read_b64_tr_b16 v[222:223], v203 offset:0x3000
	ds_read_b64_tr_b16 v[224:225], v203 offset:0x3800
	s_nop 0
	v_mfma_f32_32x32x16_bf16 v[0:15], v[140:143], v[226:229], v[0:15]
	ds_read_b64_tr_b16 v[226:227], v203 offset:0x3200
	ds_read_b64_tr_b16 v[228:229], v203 offset:0x3a00
	v_mfma_f32_32x32x16_bf16 v[48:63], v[140:143], v[230:233], v[48:63]
	ds_read_b64_tr_b16 v[230:231], v203 offset:0x3400
	ds_read_b64_tr_b16 v[232:233], v203 offset:0x3c00
	v_mfma_f32_32x32x16_bf16 v[32:47], v[140:143], v[234:237], v[32:47]
	ds_read_b64_tr_b16 v[234:235], v203 offset:0x3600
	ds_read_b64_tr_b16 v[236:237], v203 offset:0x3e00
	s_waitcnt lgkmcnt(8)
	s_nop 0
	s_waitcnt lgkmcnt(0)
	v_mfma_f32_32x32x16_bf16 v[16:31], v[140:143], v[238:241], v[16:31]
	v_add_f32_e32 v140, 0, v112
	v_add_f32_e32 v140, v113, v140
	v_add_f32_e32 v140, v114, v140
	v_add_f32_e32 v140, v115, v140
	v_add_f32_e32 v140, v116, v140
	v_add_f32_e32 v140, v117, v140
	v_add_f32_e32 v140, v118, v140
	v_mfma_f32_32x32x16_bf16 v[0:15], v[182:185], v[144:147], v[0:15]
	v_add_f32_e32 v140, v119, v140
	v_add_f32_e32 v140, v120, v140
	v_add_f32_e32 v140, v121, v140
	v_add_f32_e32 v140, v122, v140
	v_add_f32_e32 v140, v123, v140
	v_add_f32_e32 v140, v124, v140
	v_add_f32_e32 v140, v125, v140
	v_mfma_f32_32x32x16_bf16 v[48:63], v[182:185], v[186:189], v[48:63]
	v_add_f32_e32 v140, v126, v140
	v_add_f32_e32 v165, v127, v140
	v_cvt_pk_bf16_f32 v144, v112, v113
	v_cvt_pk_bf16_f32 v145, v114, v115
	v_cvt_pk_bf16_f32 v146, v116, v117
	v_cvt_pk_bf16_f32 v147, v118, v119
	v_cvt_pk_bf16_f32 v140, v120, v121
	v_mfma_f32_32x32x16_bf16 v[32:47], v[182:185], v[214:217], v[32:47]
	v_cvt_pk_bf16_f32 v141, v122, v123
	v_cvt_pk_bf16_f32 v142, v124, v125
	v_cvt_pk_bf16_f32 v143, v126, v127
	v_mfma_f32_32x32x16_bf16 v[16:31], v[182:185], v[218:221], v[16:31]
	s_waitcnt lgkmcnt(0)
	s_barrier
	v_mfma_f32_32x32x16_bf16 v[0:15], v[160:163], v[222:225], v[0:15]
	v_mfma_f32_32x32x16_bf16 v[48:63], v[160:163], v[226:229], v[48:63]
	v_mfma_f32_32x32x16_bf16 v[32:47], v[160:163], v[230:233], v[32:47]
	v_mfma_f32_32x32x16_bf16 v[16:31], v[160:163], v[234:237], v[16:31]
	v_add_u32_e32 v208, s101, v208
	v_add_u32_e32 v209, s101, v209
	v_add_u32_e32 v210, s101, v210
	v_add_u32_e32 v211, s101, v211
	ds_read_b128 v[160:163], v208 offset:32768
	ds_read_b128 v[214:217], v204 offset:51200
	ds_read_b128 v[218:221], v204 offset:52224
	ds_read_b128 v[222:225], v208 offset:36864
	v_exp_f32_e32 v166, v84
	v_exp_f32_e32 v167, v85
	s_waitcnt lgkmcnt(2)
	v_mfma_f32_32x32x16_bf16 v[112:127], v[160:163], v[214:217], v[96:111]
	ds_read_b128 v[160:163], v209 offset:32768
	ds_read_b128 v[226:229], v209 offset:36864
	ds_read_b128 v[230:233], v204 offset:53248
	ds_read_b128 v[234:237], v204 offset:54272
	ds_read_b128 v[238:241], v210 offset:36864
	ds_read_b128 v[182:185], v210 offset:32768
	ds_read_b128 v[242:245], v211 offset:36864
	ds_read_b128 v[188:191], v211 offset:32768
	v_exp_f32_e32 v186, v90
	v_exp_f32_e32 v187, v91
	s_andn2_b64 s[0:1], s[6:7], exec
	s_and_b64 s[6:7], s[8:9], exec
	s_or_b64 s[6:7], s[0:1], s[6:7]
	s_waitcnt lgkmcnt(7)
	v_mfma_f32_32x32x16_bf16 v[112:127], v[160:163], v[218:221], v[112:127]
	v_exp_f32_e32 v160, v80
	v_exp_f32_e32 v161, v81
	v_exp_f32_e32 v162, v82
	v_exp_f32_e32 v163, v83
	v_add_f32_e32 v80, v160, v165
	v_add_f32_e32 v80, v161, v80
	v_add_f32_e32 v165, v162, v80
	s_waitcnt lgkmcnt(2)
	v_mfma_f32_32x32x16_bf16 v[112:127], v[182:185], v[230:233], v[112:127]
	v_exp_f32_e32 v182, v86
	v_exp_f32_e32 v183, v87
	v_exp_f32_e32 v184, v88
	v_exp_f32_e32 v185, v89
	v_add_f32_e32 v165, v163, v165
	v_add_f32_e32 v165, v166, v165
	v_add_f32_e32 v165, v167, v165
	s_waitcnt lgkmcnt(0)
	v_mfma_f32_32x32x16_bf16 v[112:127], v[188:191], v[234:237], v[112:127]
	v_exp_f32_e32 v188, v92
	v_exp_f32_e32 v189, v93
	v_exp_f32_e32 v190, v94
	v_exp_f32_e32 v191, v95
	v_add_f32_e32 v165, v182, v165
	v_add_f32_e32 v165, v183, v165
	v_add_f32_e32 v165, v184, v165
	v_mfma_f32_32x32x16_bf16 v[80:95], v[222:225], v[214:217], v[96:111]
	v_add_f32_e32 v165, v185, v165
	v_add_f32_e32 v165, v186, v165
	v_add_f32_e32 v165, v187, v165
	v_add_f32_e32 v165, v188, v165
	v_add_f32_e32 v165, v189, v165
	v_add_f32_e32 v165, v190, v165
	v_add_f32_e32 v165, v191, v165
	v_mfma_f32_32x32x16_bf16 v[80:95], v[226:229], v[218:221], v[80:95]
	v_mov_b32_e32 v179, v165
	s_nop 1
	v_permlane32_swap_b32_e32 v165, v179
	v_add_f32_e64 v178, v164, v178
	v_add_f32_e64 v179, v165, v179
	v_cmp_ge_f32_e32 vcc, s99, v179
	s_cmp_eq_u64 vcc, exec
	v_mfma_f32_32x32x16_bf16 v[80:95], v[238:241], v[230:233], v[80:95]
	v_mfma_f32_32x32x16_bf16 v[80:95], v[242:245], v[234:237], v[80:95]
	s_cbranch_scc0 .LBB0_408

.LBB0_411:
	v_mov_b64_e32 v[64:65], v[96:97]
	v_mov_b64_e32 v[66:67], v[98:99]
	v_mov_b64_e32 v[68:69], v[100:101]
	v_mov_b64_e32 v[70:71], v[102:103]
	v_mov_b64_e32 v[72:73], v[104:105]
	v_mov_b64_e32 v[74:75], v[106:107]
	v_mov_b64_e32 v[76:77], v[108:109]
	v_mov_b64_e32 v[78:79], v[110:111]
	ds_read_b128 v[120:123], v204 offset:52224
	ds_read_b128 v[124:127], v204 offset:53248
	ds_read_b128 v[128:131], v204 offset:54272
	ds_read_b128 v[132:135], v208 offset:45056
	ds_read_b128 v[112:115], v208 offset:40960
	ds_read_b128 v[136:139], v204 offset:51200
	v_exp_f32_e32 v118, v82
	v_exp_f32_e32 v119, v83
	v_exp_f32_e32 v116, v84
	v_exp_f32_e32 v117, v85
	s_waitcnt lgkmcnt(0)
	v_mfma_f32_32x32x16_bf16 v[96:111], v[112:115], v[136:139], v[64:79]
	ds_read_b128 v[148:151], v209 offset:45056
	ds_read_b128 v[112:115], v209 offset:40960
	v_exp_f32_e32 v84, v92
	v_exp_f32_e32 v85, v93
	v_exp_f32_e32 v82, v94
	v_exp_f32_e32 v83, v95
	s_waitcnt lgkmcnt(0)
	v_mfma_f32_32x32x16_bf16 v[96:111], v[112:115], v[120:123], v[96:111]
	ds_read_b128 v[152:155], v210 offset:45056
	ds_read_b128 v[112:115], v210 offset:40960
	s_waitcnt lgkmcnt(0)
	v_mfma_f32_32x32x16_bf16 v[96:111], v[112:115], v[124:127], v[96:111]
	ds_read_b128 v[156:159], v211 offset:45056
	ds_read_b128 v[112:115], v211 offset:40960
	v_mfma_f32_32x32x16_bf16 v[64:79], v[132:135], v[136:139], v[64:79]
	s_waitcnt lgkmcnt(0)
	v_mfma_f32_32x32x16_bf16 v[96:111], v[112:115], v[128:131], v[96:111]
	v_exp_f32_e32 v112, v80
	v_exp_f32_e32 v113, v81
	v_exp_f32_e32 v80, v88
	v_exp_f32_e32 v114, v86
	v_add_f32_e32 v88, v112, v164
	v_add_f32_e32 v88, v113, v88
	v_add_f32_e32 v88, v118, v88
	v_mfma_f32_32x32x16_bf16 v[64:79], v[148:151], v[120:123], v[64:79]
	v_exp_f32_e32 v115, v87
	v_add_f32_e32 v88, v119, v88
	v_add_f32_e32 v88, v116, v88
	v_exp_f32_e32 v81, v89
	v_add_f32_e32 v88, v117, v88
	v_exp_f32_e32 v86, v90
	v_add_f32_e32 v88, v114, v88
	v_mfma_f32_32x32x16_bf16 v[64:79], v[152:155], v[124:127], v[64:79]
	v_exp_f32_e32 v87, v91
	v_add_f32_e32 v88, v115, v88
	v_add_f32_e32 v88, v80, v88
	v_add_f32_e32 v88, v81, v88
	v_add_f32_e32 v88, v86, v88
	v_add_f32_e32 v88, v87, v88
	v_add_f32_e32 v88, v84, v88
	v_add_f32_e32 v88, v85, v88
	v_mfma_f32_32x32x16_bf16 v[64:79], v[156:159], v[128:131], v[64:79]
	v_add_f32_e32 v88, v82, v88
	v_add_f32_e32 v88, v83, v88
	v_mov_b32_e32 v89, v88
	s_nop 1
	v_permlane32_swap_b32_e32 v88, v89
	v_add_f32_e32 v88, v88, v89
	v_cmp_ge_f32_e32 vcc, s99, v88
	s_cmp_lg_u64 vcc, exec
	s_cbranch_scc1 .LBB0_450
